# code placement: the four GEMM K-loop heads padded back to the baseline object's byte phase (mod 64) with s_nop in once-per-phase code
# baseline (speedup 1.0000x reference)
.LBB0_89:
	s_nop 0
	s_nop 0
	s_nop 0
	s_nop 0
	s_nop 0
	s_nop 0
	s_nop 0
	s_nop 0
	s_nop 0
	s_nop 0
	s_nop 0
	s_nop 0
	s_nop 0
	s_nop 0
	s_add_u32 s1, s82, 0x14000000
	s_mov_b64 s[20:21], s[60:61]
	v_writelane_b32 v254, s1, 0
	s_addc_u32 s1, s83, 0
	s_mov_b64 s[12:13], s[52:53]
	v_writelane_b32 v254, s1, 1
	s_mov_b64 s[22:23], s[62:63]
	s_mov_b64 s[24:25], s[64:65]
	s_mov_b64 s[14:15], s[54:55]
	v_writelane_b32 v254, s12, 2
	s_andn2_b64 vcc, exec, s[4:5]
	s_nop 0
	v_writelane_b32 v254, s13, 3
	v_writelane_b32 v254, s14, 4
	v_writelane_b32 v254, s15, 5
	v_writelane_b32 v254, s16, 6
	v_writelane_b32 v254, s17, 7
	v_writelane_b32 v254, s18, 8
	v_writelane_b32 v254, s19, 9
	v_writelane_b32 v254, s20, 10
	v_writelane_b32 v254, s21, 11
	v_writelane_b32 v254, s22, 12
	v_writelane_b32 v254, s23, 13
	v_writelane_b32 v254, s24, 14
	v_writelane_b32 v254, s25, 15
	v_writelane_b32 v254, s26, 16
	v_writelane_b32 v254, s27, 17
	s_cbranch_vccnz .LBB0_271
	v_ashrrev_i32_e32 v1, 31, v8
	v_lshrrev_b32_e32 v1, 26, v1
	v_add_u32_e32 v1, v8, v1
	v_ashrrev_i32_e32 v9, 6, v1
	v_bfe_i32 v1, v8, 27, 1
	v_lshlrev_b32_e32 v0, 4, v8
	v_lshrrev_b32_e32 v1, 22, v1
	v_add_u32_e32 v1, v0, v1
	v_and_b32_e32 v1, 0xfffffc00, v1
	v_sub_u32_e32 v1, v0, v1
	v_lshrrev_b32_e32 v2, 4, v1
	v_bitop3_b32 v1, v2, v1, 32 bitop3:0x6c
	v_ashrrev_i32_e32 v3, 31, v1
	v_lshrrev_b32_e32 v3, 26, v3
	v_add_u32_e32 v3, v1, v3
	v_lshlrev_b32_e32 v2, 3, v9
	v_ashrrev_i32_e32 v10, 6, v3
	v_and_b32_e32 v3, 0xc0, v3
	v_and_b32_e32 v2, -16, v2
	v_sub_u32_e32 v1, v1, v3
	v_mov_b32_e32 v3, 1
	v_add_u32_e32 v2, v10, v2
	v_ashrrev_i16_sdwa v1, v3, sext(v1) dst_sel:DWORD dst_unused:UNUSED_PAD src0_sel:DWORD src1_sel:BYTE_0
	v_lshlrev_b32_e32 v4, 5, v9
	v_bfe_i32 v11, v1, 0, 16
	v_lshlrev_b32_e32 v1, 1, v2
	v_lshrrev_b32_e32 v5, 2, v2
	v_and_b32_e32 v6, 3, v10
	s_mov_b32 s2, 0x1fffe0
	v_and_b32_e32 v4, 32, v4
	v_and_b32_e32 v1, 24, v1
	v_and_b32_e32 v5, 4, v5
	v_and_or_b32 v6, v2, s2, v6
	v_or3_b32 v1, v6, v5, v1
	v_add_lshl_u32 v4, v4, v11, 1
	v_add_u32_e32 v0, 0x2000, v0
	v_lshl_add_u32 v154, v1, 11, v4
	v_ashrrev_i32_e32 v1, 31, v0
	v_lshrrev_b32_e32 v1, 22, v1
	v_add_u32_e32 v1, v0, v1
	v_ashrrev_i32_e32 v12, 10, v1
	v_mul_i32_i24_e32 v1, 0x400, v12
	v_sub_u32_e32 v0, v0, v1
	v_lshrrev_b32_e32 v1, 4, v0
	v_bitop3_b32 v0, v1, v0, 32 bitop3:0x6c
	v_lshl_add_u32 v152, v2, 11, v4
	v_ashrrev_i32_e32 v2, 31, v0
	v_lshrrev_b32_e32 v2, 26, v2
	v_add_u32_e32 v2, v0, v2
	v_lshlrev_b32_e32 v1, 3, v12
	v_ashrrev_i32_e32 v13, 6, v2
	v_and_b32_e32 v2, 0xc0, v2
	s_add_u32 s44, s80, 0x8000000
	v_and_b32_e32 v1, -16, v1
	v_sub_u32_e32 v0, v0, v2
	s_addc_u32 s45, s81, 0
	s_ashr_i32 s1, s0, 6
	v_add_u32_e32 v1, v13, v1
	v_ashrrev_i16_sdwa v0, v3, sext(v0) dst_sel:DWORD dst_unused:UNUSED_PAD src0_sel:DWORD src1_sel:BYTE_0
	v_and_b32_e32 v3, 3, v13
	s_ashr_i32 s7, s6, 31
	s_ashr_i32 s19, s18, 31
	v_and_or_b32 v3, v1, s2, v3
	s_ashr_i32 s2, s0, 8
	s_lshl_b32 s46, s1, 10
	s_lshl_b64 s[4:5], s[6:7], 19
	s_lshl_b64 s[8:9], s[18:19], 19
	s_add_u32 s10, s44, s8
	v_lshlrev_b32_e32 v4, 5, v12
	v_bfe_i32 v14, v0, 0, 16
	v_lshlrev_b32_e32 v0, 1, v1
	v_lshrrev_b32_e32 v2, 2, v1
	s_addc_u32 s11, s45, s9
	s_add_i32 s19, s46, 0
	v_and_b32_e32 v4, 32, v4
	v_and_b32_e32 v0, 24, v0
	v_and_b32_e32 v2, 4, v2
	s_add_i32 m0, s19, 0x10000
	v_or3_b32 v0, v3, v2, v0
	v_add_lshl_u32 v2, v4, v14, 1
	global_load_lds_dwordx4 v154, s[10:11]
	s_add_i32 m0, s19, 0x12000
	v_lshl_add_u32 v158, v0, 11, v2
	s_add_u32 s8, s10, 0x40000
	global_load_lds_dwordx4 v158, s[10:11]
	s_addc_u32 s9, s11, 0
	s_add_i32 m0, s19, 0x14000
	v_lshl_add_u32 v156, v1, 11, v2
	global_load_lds_dwordx4 v154, s[8:9]
	s_add_i32 m0, s19, 0x16000
	v_mov_b32_e32 v161, 0
	global_load_lds_dwordx4 v158, s[8:9]
	s_add_u32 s8, s80, s4
	s_addc_u32 s9, s81, s5
	s_add_i32 s47, s19, 0x2000
	s_mov_b32 m0, s19
	s_add_u32 s4, s8, 0x40000
	global_load_lds_dwordx4 v152, s[8:9]
	s_mov_b32 m0, s47
	s_addc_u32 s5, s9, 0
	s_add_i32 s48, s19, 0x4000
	global_load_lds_dwordx4 v156, s[8:9]
	s_mov_b32 m0, s48
	s_add_i32 s49, s19, 0x6000
	global_load_lds_dwordx4 v152, s[4:5]
	s_mov_b32 m0, s49
	v_mov_b32_e32 v155, v161
	global_load_lds_dwordx4 v156, s[4:5]
	v_mov_b32_e32 v159, v161
	v_mov_b32_e32 v153, v161
	v_mov_b32_e32 v157, v161
	s_cmp_eq_u32 s2, 1
	s_mov_b32 s21, 0
	v_lshl_add_u64 v[6:7], s[10:11], 0, v[154:155]
	v_lshl_add_u64 v[4:5], s[10:11], 0, v[158:159]
	v_lshl_add_u64 v[0:1], s[8:9], 0, v[152:153]
	s_cselect_b64 s[22:23], -1, 0
	s_cmp_lg_u32 s2, 1
	v_lshl_add_u64 v[2:3], s[8:9], 0, v[156:157]
	s_cbranch_scc1 .LBB0_92
	s_barrier

.LBB0_624:
	s_or_b64 exec, exec, s[4:5]
	s_cmpk_lt_i32 s88, 0x400
	s_waitcnt lgkmcnt(0)
	s_barrier
	s_nop 0
	s_nop 0
	s_nop 0
	s_nop 0
	s_nop 0
	s_nop 0
	s_nop 0
	s_nop 0
	s_nop 0
	s_nop 0
	v_mov_b32 v8, v145
	s_cselect_b64 s[4:5], -1, 0
	s_cmpk_gt_i32 s88, 0x3ff
	v_readfirstlane_b32 s18, v8
	s_cbranch_scc1 .LBB0_630
	s_ashr_i32 s0, s88, 31
	s_lshr_b32 s0, s0, 29
	s_add_i32 s0, s88, s0
	s_and_b32 s1, s0, -8
	s_sub_i32 s1, s88, s1
	s_cmp_gt_i32 s1, -1
	s_cbranch_scc0 .LBB0_627
	s_lshl_b32 s2, s1, 7
	s_cbranch_execz .LBB0_628
	s_branch .LBB0_629
